# v35 + ffn_in epilogues: per-store v_add_co/s_nop/v_addc address pairs replaced by one v_lshl_add_u64 with s[48:49]
# speedup vs baseline: 1.0061x; 1.0061x over previous
; DEV float silu(float x) { return x * sigm(x); }
; template <bool RES, class Epi>
; DEV void gemm_tile_x(const bf16_t* A0, int lda0, const bf16_t* A1, int lda1, int ksplit,
;                      const bf16_t* Bt, int ldb, int K, char* smem, const float* resb, Epi epi) {
;     ...
;       for (int r8 = 0; r8 < 8; ++r8) {
;         const int r = rh * 8 + r8;
;         const int ru = mi * 32 + (r & 3) + 8 * (r >> 2);
;         if (RES) epi(ru, rl, col, acc[mi][0][r], acc[mi][1][r], x0[r8], x1[r8]);
;         else epi(ru, rl, col, acc[mi][0][r], acc[mi][1][r], 0.f, 0.f);
;         if ((r8 & 3) == 3) __builtin_amdgcn_sched_barrier(0);
; DEV void phase_ffn_in(const Params& p, const bf16_t* wt, char* smem) {
;     ...
;               [&](int ru, int rl, int c, float v0, float v1) {
;                 (hb + ru * DFF)[(unsigned)(rl * DFF + (c >> 6) * 32 + (c & 31))] = f2bf(silu(v0) * v1);
;               });
.LBB0_174:
	s_waitcnt vmcnt(5)
	v_mul_f32_e32 v128, 0xbfb8aa3b, v112
	v_exp_f32_e32 v128, v128
	s_lshl_b32 s52, s52, 6
	s_mul_hi_u32 s54, s48, 0x160000
	s_mul_i32 s48, s48, 0x160000
	v_add_f32_e32 v128, 1.0, v128
	v_rcp_f32_e32 v128, v128
	s_ashr_i32 s53, s52, 31
	s_add_u32 s48, s84, s48
	s_addc_u32 s54, s85, s54
	s_lshl_b64 s[52:53], s[52:53], 1
	s_add_u32 s52, s48, s52
	v_mul_f32_e32 v112, v112, v128
	s_addc_u32 s53, s54, s53
	v_mul_f32_e32 v96, v96, v112
	v_cvt_pk_bf16_f32 v96, v96, s0
	v_lshl_add_u64 v[128:129], v[182:183], 1, s[52:53]
	global_store_short v[128:129], v96, off
	v_mul_f32_e32 v96, 0xbfb8aa3b, v113
	v_exp_f32_e32 v96, v96
	s_movk_i32 s48, 0x1000
	v_add_f32_e32 v96, 1.0, v96
	v_rcp_f32_e32 v96, v96
	s_nop 0
	v_mul_f32_e32 v96, v113, v96
	v_mul_f32_e32 v96, v97, v96
	v_cvt_pk_bf16_f32 v112, v96, s0
	v_lshl_add_u64 v[96:97], v[128:129], 0, s[48:49]
	s_movk_i32 s48, 0x2000
	s_nop 0
	global_store_short v[96:97], v112, off offset:1536
	v_mul_f32_e32 v96, 0xbfb8aa3b, v114
	v_exp_f32_e32 v96, v96
	s_nop 0
	v_add_f32_e32 v96, 1.0, v96
	v_rcp_f32_e32 v96, v96
	s_nop 0
	v_mul_f32_e32 v96, v114, v96
	v_mul_f32_e32 v96, v98, v96
	v_cvt_pk_bf16_f32 v98, v96, s0
	v_lshl_add_u64 v[96:97], v[128:129], 0, s[48:49]
	s_movk_i32 s48, 0x4000
	s_nop 0
	global_store_short v[96:97], v98, off offset:3072
	v_mul_f32_e32 v96, 0xbfb8aa3b, v115
	v_exp_f32_e32 v96, v96
	s_nop 0
	v_add_f32_e32 v96, 1.0, v96
	v_rcp_f32_e32 v96, v96
	s_nop 0
	v_mul_f32_e32 v96, v115, v96
	v_mul_f32_e32 v96, v99, v96
	v_cvt_pk_bf16_f32 v98, v96, s0
	v_lshl_add_u64 v[96:97], v[128:129], 0, s[48:49]
	global_store_short v[96:97], v98, off offset:512
	v_mul_f32_e32 v96, 0xbfb8aa3b, v116
	v_exp_f32_e32 v96, v96
	s_mov_b32 s48, 0xb000
	v_add_f32_e32 v96, 1.0, v96
	v_rcp_f32_e32 v96, v96
	s_nop 0
	v_mul_f32_e32 v96, v116, v96
	v_mul_f32_e32 v96, v100, v96
	v_cvt_pk_bf16_f32 v98, v96, s0
	v_lshl_add_u64 v[96:97], v[128:129], 0, s[48:49]
	s_mov_b32 s48, 0xc000
	s_nop 0
	global_store_short v[96:97], v98, off
	v_mul_f32_e32 v96, 0xbfb8aa3b, v117
	v_exp_f32_e32 v96, v96
	s_nop 0
	v_add_f32_e32 v96, 1.0, v96
	v_rcp_f32_e32 v96, v96
	s_nop 0
	v_mul_f32_e32 v96, v117, v96
	v_mul_f32_e32 v96, v101, v96
	v_cvt_pk_bf16_f32 v98, v96, s0
	v_lshl_add_u64 v[96:97], v[128:129], 0, s[48:49]
	s_mov_b32 s48, 0xd000
	s_nop 0
	global_store_short v[96:97], v98, off offset:1536
	v_mul_f32_e32 v96, 0xbfb8aa3b, v118
	v_exp_f32_e32 v96, v96
	s_nop 0
	v_add_f32_e32 v96, 1.0, v96
	v_rcp_f32_e32 v96, v96
	s_nop 0
	v_mul_f32_e32 v96, v118, v96
	v_mul_f32_e32 v96, v102, v96
	v_cvt_pk_bf16_f32 v98, v96, s0
	v_lshl_add_u64 v[96:97], v[128:129], 0, s[48:49]
	s_mov_b32 s48, 0xf000
	s_nop 0
	global_store_short v[96:97], v98, off offset:3072
	v_mul_f32_e32 v96, 0xbfb8aa3b, v119
	v_exp_f32_e32 v96, v96
	s_nop 0
	v_add_f32_e32 v96, 1.0, v96
	v_rcp_f32_e32 v96, v96
	s_nop 0
	v_mul_f32_e32 v96, v119, v96
	v_mul_f32_e32 v96, v103, v96
	v_cvt_pk_bf16_f32 v98, v96, s0
	v_lshl_add_u64 v[96:97], v[128:129], 0, s[48:49]
	global_store_short v[96:97], v98, off offset:512
	v_mul_f32_e32 v96, 0xbfb8aa3b, v120
	v_exp_f32_e32 v96, v96
	s_mov_b32 s48, 0x16000
	v_add_f32_e32 v96, 1.0, v96
	v_rcp_f32_e32 v96, v96
	s_nop 0
	v_mul_f32_e32 v96, v120, v96
	v_mul_f32_e32 v96, v104, v96
	v_cvt_pk_bf16_f32 v98, v96, s0
	v_lshl_add_u64 v[96:97], v[128:129], 0, s[48:49]
	s_mov_b32 s48, 0x17000
	s_nop 0
	global_store_short v[96:97], v98, off
	v_mul_f32_e32 v96, 0xbfb8aa3b, v121
	v_exp_f32_e32 v96, v96
	s_nop 0
	v_add_f32_e32 v96, 1.0, v96
	v_rcp_f32_e32 v96, v96
	s_nop 0
	v_mul_f32_e32 v96, v121, v96
	v_mul_f32_e32 v96, v105, v96
	v_cvt_pk_bf16_f32 v98, v96, s0
	v_lshl_add_u64 v[96:97], v[128:129], 0, s[48:49]
	s_mov_b32 s48, 0x18000
	s_nop 0
	global_store_short v[96:97], v98, off offset:1536
	v_mul_f32_e32 v96, 0xbfb8aa3b, v122
	v_exp_f32_e32 v96, v96
	s_nop 0
	v_add_f32_e32 v96, 1.0, v96
	v_rcp_f32_e32 v96, v96
	s_nop 0
	v_mul_f32_e32 v96, v122, v96
	v_mul_f32_e32 v96, v106, v96
	v_cvt_pk_bf16_f32 v98, v96, s0
	v_lshl_add_u64 v[96:97], v[128:129], 0, s[48:49]
	s_mov_b32 s48, 0x1a000
	s_nop 0
	global_store_short v[96:97], v98, off offset:3072
	v_mul_f32_e32 v96, 0xbfb8aa3b, v123
	v_exp_f32_e32 v96, v96
	s_nop 0
	v_add_f32_e32 v96, 1.0, v96
	v_rcp_f32_e32 v96, v96
	s_nop 0
	v_mul_f32_e32 v96, v123, v96
	v_mul_f32_e32 v96, v107, v96
	v_cvt_pk_bf16_f32 v98, v96, s0
	v_lshl_add_u64 v[96:97], v[128:129], 0, s[48:49]
	global_store_short v[96:97], v98, off offset:512
	v_mul_f32_e32 v96, 0xbfb8aa3b, v124
	v_exp_f32_e32 v96, v96
	s_mov_b32 s48, 0x21000
	v_add_f32_e32 v96, 1.0, v96
	v_rcp_f32_e32 v96, v96
	s_nop 0
	v_mul_f32_e32 v96, v124, v96
	v_mul_f32_e32 v96, v108, v96
	v_cvt_pk_bf16_f32 v98, v96, s0
	v_lshl_add_u64 v[96:97], v[128:129], 0, s[48:49]
	s_mov_b32 s48, 0x22000
	s_nop 0
	global_store_short v[96:97], v98, off
	v_mul_f32_e32 v96, 0xbfb8aa3b, v125
	v_exp_f32_e32 v96, v96
	s_nop 0
	v_add_f32_e32 v96, 1.0, v96
	v_rcp_f32_e32 v96, v96
	s_nop 0
	v_mul_f32_e32 v96, v125, v96
	v_mul_f32_e32 v96, v109, v96
	v_cvt_pk_bf16_f32 v98, v96, s0
	v_lshl_add_u64 v[96:97], v[128:129], 0, s[48:49]
	s_mov_b32 s48, 0x23000
	s_nop 0
	global_store_short v[96:97], v98, off offset:1536
	v_mul_f32_e32 v96, 0xbfb8aa3b, v126
	v_exp_f32_e32 v96, v96
	s_nop 0
	v_add_f32_e32 v96, 1.0, v96
	v_rcp_f32_e32 v96, v96
	s_nop 0
	v_mul_f32_e32 v96, v126, v96
	v_mul_f32_e32 v96, v110, v96
	v_cvt_pk_bf16_f32 v98, v96, s0
	v_lshl_add_u64 v[96:97], v[128:129], 0, s[48:49]
	s_mov_b32 s48, 0x25000
	s_nop 0
	global_store_short v[96:97], v98, off offset:3072
	v_mul_f32_e32 v96, 0xbfb8aa3b, v127
	v_exp_f32_e32 v96, v96
	s_nop 0
	v_add_f32_e32 v96, 1.0, v96
	v_rcp_f32_e32 v96, v96
; DEV float silu(float x) { return x * sigm(x); }
; template <bool RES, class Epi>
; DEV void gemm_tile_x(const bf16_t* A0, int lda0, const bf16_t* A1, int lda1, int ksplit,
;                      const bf16_t* Bt, int ldb, int K, char* smem, const float* resb, Epi epi) {
;     ...
;       for (int r8 = 0; r8 < 8; ++r8) {
;         const int r = rh * 8 + r8;
;         const int ru = mi * 32 + (r & 3) + 8 * (r >> 2);
;         if (RES) epi(ru, rl, col, acc[mi][0][r], acc[mi][1][r], x0[r8], x1[r8]);
;         else epi(ru, rl, col, acc[mi][0][r], acc[mi][1][r], 0.f, 0.f);
;         if ((r8 & 3) == 3) __builtin_amdgcn_sched_barrier(0);
; DEV void phase_ffn_in(const Params& p, const bf16_t* wt, char* smem) {
;     ...
;               [&](int ru, int rl, int c, float v0, float v1) {
;                 (hb + ru * DFF)[(unsigned)(rl * DFF + (c >> 6) * 32 + (c & 31))] = f2bf(silu(v0) * v1);
;               });
	s_nop 0
	v_mul_f32_e32 v96, v127, v96
	v_mul_f32_e32 v96, v111, v96
	v_cvt_pk_bf16_f32 v98, v96, s0
	v_lshl_add_u64 v[96:97], v[128:129], 0, s[48:49]
	global_store_short v[96:97], v98, off offset:512
	v_mul_f32_e32 v96, 0xbfb8aa3b, v80
	v_exp_f32_e32 v96, v96
	s_mov_b32 s48, 0x2c000
	v_add_f32_e32 v96, 1.0, v96
	v_rcp_f32_e32 v96, v96
	s_nop 0
	v_mul_f32_e32 v80, v80, v96
	v_mul_f32_e32 v64, v64, v80
	v_lshl_add_u64 v[96:97], v[128:129], 0, s[48:49]
	v_cvt_pk_bf16_f32 v64, v64, s0
	s_nop 0
	global_store_short v[96:97], v64, off
	v_mul_f32_e32 v64, 0xbfb8aa3b, v81
	v_exp_f32_e32 v64, v64
	s_mov_b32 s48, 0x2d000
	v_add_f32_e32 v64, 1.0, v64
	v_rcp_f32_e32 v64, v64
	s_nop 0
	v_mul_f32_e32 v64, v81, v64
	v_mul_f32_e32 v64, v65, v64
	v_cvt_pk_bf16_f32 v80, v64, s0
	v_lshl_add_u64 v[64:65], v[128:129], 0, s[48:49]
	s_mov_b32 s48, 0x2e000
	s_nop 0
	global_store_short v[64:65], v80, off offset:1536
	v_mul_f32_e32 v64, 0xbfb8aa3b, v82
	v_exp_f32_e32 v64, v64
	s_nop 0
	v_add_f32_e32 v64, 1.0, v64
	v_rcp_f32_e32 v64, v64
	s_nop 0
	v_mul_f32_e32 v64, v82, v64
	v_mul_f32_e32 v64, v66, v64
	v_cvt_pk_bf16_f32 v66, v64, s0
	v_lshl_add_u64 v[64:65], v[128:129], 0, s[48:49]
	s_mov_b32 s48, 0x30000
	s_nop 0
	global_store_short v[64:65], v66, off offset:3072
	v_mul_f32_e32 v64, 0xbfb8aa3b, v83
	v_exp_f32_e32 v64, v64
	s_nop 0
	v_add_f32_e32 v64, 1.0, v64
	v_rcp_f32_e32 v64, v64
	s_nop 0
	v_mul_f32_e32 v64, v83, v64
	v_mul_f32_e32 v64, v67, v64
	v_cvt_pk_bf16_f32 v66, v64, s0
	v_lshl_add_u64 v[64:65], v[128:129], 0, s[48:49]
	global_store_short v[64:65], v66, off offset:512
	v_mul_f32_e32 v64, 0xbfb8aa3b, v84
	v_exp_f32_e32 v64, v64
	s_mov_b32 s48, 0x37000
	v_add_f32_e32 v64, 1.0, v64
	v_rcp_f32_e32 v64, v64
	s_nop 0
	v_mul_f32_e32 v64, v84, v64
	v_mul_f32_e32 v64, v68, v64
	v_cvt_pk_bf16_f32 v66, v64, s0
	v_lshl_add_u64 v[64:65], v[128:129], 0, s[48:49]
	s_mov_b32 s48, 0x38000
	s_nop 0
	global_store_short v[64:65], v66, off
	v_mul_f32_e32 v64, 0xbfb8aa3b, v85
	v_exp_f32_e32 v64, v64
	s_nop 0
	v_add_f32_e32 v64, 1.0, v64
	v_rcp_f32_e32 v64, v64
	s_nop 0
	v_mul_f32_e32 v64, v85, v64
	v_mul_f32_e32 v64, v69, v64
	v_cvt_pk_bf16_f32 v66, v64, s0
	v_lshl_add_u64 v[64:65], v[128:129], 0, s[48:49]
	s_mov_b32 s48, 0x39000
	s_nop 0
	global_store_short v[64:65], v66, off offset:1536
	v_mul_f32_e32 v64, 0xbfb8aa3b, v86
	v_exp_f32_e32 v64, v64
	s_nop 0
	v_add_f32_e32 v64, 1.0, v64
	v_rcp_f32_e32 v64, v64
	s_nop 0
	v_mul_f32_e32 v64, v86, v64
	v_mul_f32_e32 v64, v70, v64
	v_cvt_pk_bf16_f32 v66, v64, s0
	v_lshl_add_u64 v[64:65], v[128:129], 0, s[48:49]
	s_mov_b32 s48, 0x3b000
	s_nop 0
	global_store_short v[64:65], v66, off offset:3072
	v_mul_f32_e32 v64, 0xbfb8aa3b, v87
	v_exp_f32_e32 v64, v64
	s_nop 0
	v_add_f32_e32 v64, 1.0, v64
	v_rcp_f32_e32 v64, v64
	s_nop 0
	v_mul_f32_e32 v64, v87, v64
	v_mul_f32_e32 v64, v71, v64
	v_cvt_pk_bf16_f32 v66, v64, s0
	v_lshl_add_u64 v[64:65], v[128:129], 0, s[48:49]
	global_store_short v[64:65], v66, off offset:512
	v_mul_f32_e32 v64, 0xbfb8aa3b, v88
	v_exp_f32_e32 v64, v64
	s_mov_b32 s48, 0x42000
	v_add_f32_e32 v64, 1.0, v64
	v_rcp_f32_e32 v64, v64
	s_nop 0
	v_mul_f32_e32 v64, v88, v64
	v_mul_f32_e32 v64, v72, v64
	v_cvt_pk_bf16_f32 v66, v64, s0
	v_lshl_add_u64 v[64:65], v[128:129], 0, s[48:49]
	s_mov_b32 s48, 0x43000
	s_nop 0
	global_store_short v[64:65], v66, off
	v_mul_f32_e32 v64, 0xbfb8aa3b, v89
	v_exp_f32_e32 v64, v64
	s_nop 0
	v_add_f32_e32 v64, 1.0, v64
	v_rcp_f32_e32 v64, v64
	s_nop 0
	v_mul_f32_e32 v64, v89, v64
	v_mul_f32_e32 v64, v73, v64
	v_cvt_pk_bf16_f32 v66, v64, s0
	v_lshl_add_u64 v[64:65], v[128:129], 0, s[48:49]
	s_mov_b32 s48, 0x44000
	s_nop 0
	global_store_short v[64:65], v66, off offset:1536
	v_mul_f32_e32 v64, 0xbfb8aa3b, v90
	v_exp_f32_e32 v64, v64
	s_nop 0
	v_add_f32_e32 v64, 1.0, v64
	v_rcp_f32_e32 v64, v64
	s_nop 0
	v_mul_f32_e32 v64, v90, v64
	v_mul_f32_e32 v64, v74, v64
	v_cvt_pk_bf16_f32 v66, v64, s0
	v_lshl_add_u64 v[64:65], v[128:129], 0, s[48:49]
	s_mov_b32 s48, 0x46000
	s_nop 0
	global_store_short v[64:65], v66, off offset:3072
	v_mul_f32_e32 v64, 0xbfb8aa3b, v91
	v_exp_f32_e32 v64, v64
	s_nop 0
	v_add_f32_e32 v64, 1.0, v64
	v_rcp_f32_e32 v64, v64
	s_nop 0
	v_mul_f32_e32 v64, v91, v64
	v_mul_f32_e32 v64, v75, v64
	v_cvt_pk_bf16_f32 v66, v64, s0
	v_lshl_add_u64 v[64:65], v[128:129], 0, s[48:49]
	global_store_short v[64:65], v66, off offset:512
	v_mul_f32_e32 v64, 0xbfb8aa3b, v92
	v_exp_f32_e32 v64, v64
	s_mov_b32 s48, 0x4d000
	v_add_f32_e32 v64, 1.0, v64
	v_rcp_f32_e32 v64, v64
	s_nop 0
	v_mul_f32_e32 v64, v92, v64
	v_mul_f32_e32 v64, v76, v64
	v_cvt_pk_bf16_f32 v66, v64, s0
	v_lshl_add_u64 v[64:65], v[128:129], 0, s[48:49]
	s_mov_b32 s48, 0x4e000
	s_nop 0
	global_store_short v[64:65], v66, off
	v_mul_f32_e32 v64, 0xbfb8aa3b, v93
	v_exp_f32_e32 v64, v64
	s_nop 0
	v_add_f32_e32 v64, 1.0, v64
	v_rcp_f32_e32 v64, v64
	s_nop 0
	v_mul_f32_e32 v64, v93, v64
	v_mul_f32_e32 v64, v77, v64
	v_cvt_pk_bf16_f32 v66, v64, s0
	v_lshl_add_u64 v[64:65], v[128:129], 0, s[48:49]
	s_mov_b32 s48, 0x4f000
	s_nop 0
	global_store_short v[64:65], v66, off offset:1536
	v_mul_f32_e32 v64, 0xbfb8aa3b, v94
	v_exp_f32_e32 v64, v64
	s_nop 0
	v_add_f32_e32 v64, 1.0, v64
	v_rcp_f32_e32 v64, v64
	s_nop 0
	v_mul_f32_e32 v64, v94, v64
	v_mul_f32_e32 v64, v78, v64
	v_cvt_pk_bf16_f32 v66, v64, s0
	v_lshl_add_u64 v[64:65], v[128:129], 0, s[48:49]
	s_mov_b32 s48, 0x51000
	s_nop 0
	global_store_short v[64:65], v66, off offset:3072
	v_mul_f32_e32 v64, 0xbfb8aa3b, v95
	v_exp_f32_e32 v64, v64
	s_nop 0
	v_add_f32_e32 v64, 1.0, v64
	v_rcp_f32_e32 v64, v64
	s_nop 0
	v_mul_f32_e32 v64, v95, v64
	v_mul_f32_e32 v64, v79, v64
	v_cvt_pk_bf16_f32 v66, v64, s0
; DEV float silu(float x) { return x * sigm(x); }
; template <bool RES, class Epi>
; DEV void gemm_tile_x(const bf16_t* A0, int lda0, const bf16_t* A1, int lda1, int ksplit,
;                      const bf16_t* Bt, int ldb, int K, char* smem, const float* resb, Epi epi) {
;     ...
;       for (int r8 = 0; r8 < 8; ++r8) {
;         const int r = rh * 8 + r8;
;         const int ru = mi * 32 + (r & 3) + 8 * (r >> 2);
;         if (RES) epi(ru, rl, col, acc[mi][0][r], acc[mi][1][r], x0[r8], x1[r8]);
;         else epi(ru, rl, col, acc[mi][0][r], acc[mi][1][r], 0.f, 0.f);
;         if ((r8 & 3) == 3) __builtin_amdgcn_sched_barrier(0);
; DEV void phase_ffn_in(const Params& p, const bf16_t* wt, char* smem) {
;     ...
;               [&](int ru, int rl, int c, float v0, float v1) {
;                 (hb + ru * DFF)[(unsigned)(rl * DFF + (c >> 6) * 32 + (c & 31))] = f2bf(silu(v0) * v1);
;               });
	v_lshl_add_u64 v[64:65], v[128:129], 0, s[48:49]
	global_store_short v[64:65], v66, off offset:512
	v_mul_f32_e32 v64, 0xbfb8aa3b, v48
	v_exp_f32_e32 v64, v64
	s_mov_b32 s48, 0x58000
	v_add_f32_e32 v64, 1.0, v64
	v_rcp_f32_e32 v64, v64
	s_nop 0
	v_mul_f32_e32 v48, v48, v64
	v_mul_f32_e32 v32, v32, v48
	v_lshl_add_u64 v[64:65], v[128:129], 0, s[48:49]
	v_cvt_pk_bf16_f32 v32, v32, s0
	s_nop 0
	global_store_short v[64:65], v32, off
	v_mul_f32_e32 v32, 0xbfb8aa3b, v49
	v_exp_f32_e32 v32, v32
	s_mov_b32 s48, 0x59000
	v_add_f32_e32 v32, 1.0, v32
	v_rcp_f32_e32 v32, v32
	s_nop 0
	v_mul_f32_e32 v32, v49, v32
	v_mul_f32_e32 v32, v33, v32
	v_cvt_pk_bf16_f32 v48, v32, s0
	v_lshl_add_u64 v[32:33], v[128:129], 0, s[48:49]
	s_mov_b32 s48, 0x5a000
	s_nop 0
	global_store_short v[32:33], v48, off offset:1536
	v_mul_f32_e32 v32, 0xbfb8aa3b, v50
	v_exp_f32_e32 v32, v32
	s_nop 0
	v_add_f32_e32 v32, 1.0, v32
	v_rcp_f32_e32 v32, v32
	s_nop 0
	v_mul_f32_e32 v32, v50, v32
	v_mul_f32_e32 v32, v34, v32
	v_cvt_pk_bf16_f32 v34, v32, s0
	v_lshl_add_u64 v[32:33], v[128:129], 0, s[48:49]
	s_mov_b32 s48, 0x5c000
	s_nop 0
	global_store_short v[32:33], v34, off offset:3072
	v_mul_f32_e32 v32, 0xbfb8aa3b, v51
	v_exp_f32_e32 v32, v32
	s_nop 0
	v_add_f32_e32 v32, 1.0, v32
	v_rcp_f32_e32 v32, v32
	s_nop 0
	v_mul_f32_e32 v32, v51, v32
	v_mul_f32_e32 v32, v35, v32
	v_cvt_pk_bf16_f32 v34, v32, s0
	v_lshl_add_u64 v[32:33], v[128:129], 0, s[48:49]
	global_store_short v[32:33], v34, off offset:512
	v_mul_f32_e32 v32, 0xbfb8aa3b, v52
	v_exp_f32_e32 v32, v32
	s_mov_b32 s48, 0x63000
	v_add_f32_e32 v32, 1.0, v32
	v_rcp_f32_e32 v32, v32
	s_nop 0
	v_mul_f32_e32 v32, v52, v32
	v_mul_f32_e32 v32, v36, v32
	v_cvt_pk_bf16_f32 v34, v32, s0
	v_lshl_add_u64 v[32:33], v[128:129], 0, s[48:49]
	s_mov_b32 s48, 0x64000
	s_nop 0
	global_store_short v[32:33], v34, off
	v_mul_f32_e32 v32, 0xbfb8aa3b, v53
	v_exp_f32_e32 v32, v32
	s_nop 0
	v_add_f32_e32 v32, 1.0, v32
	v_rcp_f32_e32 v32, v32
	s_nop 0
	v_mul_f32_e32 v32, v53, v32
	v_mul_f32_e32 v32, v37, v32
	v_cvt_pk_bf16_f32 v34, v32, s0
	v_lshl_add_u64 v[32:33], v[128:129], 0, s[48:49]
	s_mov_b32 s48, 0x65000
	s_nop 0
	global_store_short v[32:33], v34, off offset:1536
	v_mul_f32_e32 v32, 0xbfb8aa3b, v54
	v_exp_f32_e32 v32, v32
	s_nop 0
	v_add_f32_e32 v32, 1.0, v32
	v_rcp_f32_e32 v32, v32
	s_nop 0
	v_mul_f32_e32 v32, v54, v32
	v_mul_f32_e32 v32, v38, v32
	v_cvt_pk_bf16_f32 v34, v32, s0
	v_lshl_add_u64 v[32:33], v[128:129], 0, s[48:49]
	s_mov_b32 s48, 0x67000
	s_nop 0
	global_store_short v[32:33], v34, off offset:3072
	v_mul_f32_e32 v32, 0xbfb8aa3b, v55
	v_exp_f32_e32 v32, v32
	s_nop 0
	v_add_f32_e32 v32, 1.0, v32
	v_rcp_f32_e32 v32, v32
	s_nop 0
	v_mul_f32_e32 v32, v55, v32
	v_mul_f32_e32 v32, v39, v32
	v_cvt_pk_bf16_f32 v34, v32, s0
	v_lshl_add_u64 v[32:33], v[128:129], 0, s[48:49]
	global_store_short v[32:33], v34, off offset:512
	v_mul_f32_e32 v32, 0xbfb8aa3b, v56
	v_exp_f32_e32 v32, v32
	s_mov_b32 s48, 0x6e000
	v_add_f32_e32 v32, 1.0, v32
	v_rcp_f32_e32 v32, v32
	s_nop 0
	v_mul_f32_e32 v32, v56, v32
	v_mul_f32_e32 v32, v40, v32
	v_cvt_pk_bf16_f32 v34, v32, s0
	v_lshl_add_u64 v[32:33], v[128:129], 0, s[48:49]
	s_mov_b32 s48, 0x6f000
	s_nop 0
	global_store_short v[32:33], v34, off
	v_mul_f32_e32 v32, 0xbfb8aa3b, v57
	v_exp_f32_e32 v32, v32
	s_nop 0
	v_add_f32_e32 v32, 1.0, v32
	v_rcp_f32_e32 v32, v32
	s_nop 0
	v_mul_f32_e32 v32, v57, v32
	v_mul_f32_e32 v32, v41, v32
	v_cvt_pk_bf16_f32 v34, v32, s0
	v_lshl_add_u64 v[32:33], v[128:129], 0, s[48:49]
	s_mov_b32 s48, 0x70000
	s_nop 0
	global_store_short v[32:33], v34, off offset:1536
	v_mul_f32_e32 v32, 0xbfb8aa3b, v58
	v_exp_f32_e32 v32, v32
	s_nop 0
	v_add_f32_e32 v32, 1.0, v32
	v_rcp_f32_e32 v32, v32
	s_nop 0
	v_mul_f32_e32 v32, v58, v32
	v_mul_f32_e32 v32, v42, v32
	v_cvt_pk_bf16_f32 v34, v32, s0
	v_lshl_add_u64 v[32:33], v[128:129], 0, s[48:49]
	s_mov_b32 s48, 0x72000
	s_nop 0
	global_store_short v[32:33], v34, off offset:3072
	v_mul_f32_e32 v32, 0xbfb8aa3b, v59
	v_exp_f32_e32 v32, v32
	s_nop 0
	v_add_f32_e32 v32, 1.0, v32
	v_rcp_f32_e32 v32, v32
	s_nop 0
	v_mul_f32_e32 v32, v59, v32
	v_mul_f32_e32 v32, v43, v32
	v_cvt_pk_bf16_f32 v34, v32, s0
	v_lshl_add_u64 v[32:33], v[128:129], 0, s[48:49]
	global_store_short v[32:33], v34, off offset:512
	v_mul_f32_e32 v32, 0xbfb8aa3b, v60
	v_exp_f32_e32 v32, v32
	s_mov_b32 s48, 0x79000
	v_add_f32_e32 v32, 1.0, v32
	v_rcp_f32_e32 v32, v32
	s_nop 0
	v_mul_f32_e32 v32, v60, v32
	v_mul_f32_e32 v32, v44, v32
	v_cvt_pk_bf16_f32 v34, v32, s0
	v_lshl_add_u64 v[32:33], v[128:129], 0, s[48:49]
	s_mov_b32 s48, 0x7a000
	s_nop 0
	global_store_short v[32:33], v34, off
	v_mul_f32_e32 v32, 0xbfb8aa3b, v61
	v_exp_f32_e32 v32, v32
	s_nop 0
	v_add_f32_e32 v32, 1.0, v32
	v_rcp_f32_e32 v32, v32
	s_nop 0
	v_mul_f32_e32 v32, v61, v32
	v_mul_f32_e32 v32, v45, v32
	v_cvt_pk_bf16_f32 v34, v32, s0
	v_lshl_add_u64 v[32:33], v[128:129], 0, s[48:49]
	s_mov_b32 s48, 0x7b000
	s_nop 0
	global_store_short v[32:33], v34, off offset:1536
	v_mul_f32_e32 v32, 0xbfb8aa3b, v62
	v_exp_f32_e32 v32, v32
	s_nop 0
	v_add_f32_e32 v32, 1.0, v32
	v_rcp_f32_e32 v32, v32
	s_nop 0
	v_mul_f32_e32 v32, v62, v32
	v_mul_f32_e32 v32, v46, v32
	v_cvt_pk_bf16_f32 v34, v32, s0
	v_lshl_add_u64 v[32:33], v[128:129], 0, s[48:49]
	s_mov_b32 s48, 0x7d000
	s_nop 0
	global_store_short v[32:33], v34, off offset:3072
	v_mul_f32_e32 v32, 0xbfb8aa3b, v63
	v_exp_f32_e32 v32, v32
	s_nop 0
	v_add_f32_e32 v32, 1.0, v32
	v_rcp_f32_e32 v32, v32
	s_nop 0
	v_mul_f32_e32 v32, v63, v32
	v_mul_f32_e32 v32, v47, v32
; DEV float silu(float x) { return x * sigm(x); }
; DEV bool tile_map(int it, int nct, int& rt, int& ct) {
;   const int bpx = gridDim.x >> 3, xcd = blockIdx.x & 7, j = blockIdx.x >> 3;
;   const int q = j + it * bpx;
;   if (q >= 24 * nct) return false;
; DEV void phase_ffn_in(const Params& p, const bf16_t* wt, char* smem) {
;     ...
;               [&](int ru, int rl, int c, float v0, float v1) {
;                 (hb + ru * DFF)[(unsigned)(rl * DFF + (c >> 6) * 32 + (c & 31))] = f2bf(silu(v0) * v1);
;               });
	v_cvt_pk_bf16_f32 v34, v32, s0
	v_lshl_add_u64 v[32:33], v[128:129], 0, s[48:49]
	global_store_short v[32:33], v34, off offset:512
	v_mul_f32_e32 v32, 0xbfb8aa3b, v16
	v_exp_f32_e32 v32, v32
	s_mov_b32 s48, 0x84000
	v_add_f32_e32 v32, 1.0, v32
	v_rcp_f32_e32 v32, v32
	s_nop 0
	v_mul_f32_e32 v16, v16, v32
	v_mul_f32_e32 v0, v0, v16
	v_lshl_add_u64 v[32:33], v[128:129], 0, s[48:49]
	v_cvt_pk_bf16_f32 v0, v0, s0
	s_nop 0
	global_store_short v[32:33], v0, off
	v_mul_f32_e32 v0, 0xbfb8aa3b, v17
	v_exp_f32_e32 v0, v0
	s_mov_b32 s48, 0x85000
	v_add_f32_e32 v0, 1.0, v0
	v_rcp_f32_e32 v0, v0
	s_nop 0
	v_mul_f32_e32 v0, v17, v0
	v_mul_f32_e32 v0, v1, v0
	v_cvt_pk_bf16_f32 v16, v0, s0
	v_lshl_add_u64 v[0:1], v[128:129], 0, s[48:49]
	s_mov_b32 s48, 0x86000
	s_nop 0
	global_store_short v[0:1], v16, off offset:1536
	v_mul_f32_e32 v0, 0xbfb8aa3b, v18
	v_exp_f32_e32 v0, v0
	s_nop 0
	v_add_f32_e32 v0, 1.0, v0
	v_rcp_f32_e32 v0, v0
	s_nop 0
	v_mul_f32_e32 v0, v18, v0
	v_mul_f32_e32 v0, v2, v0
	v_cvt_pk_bf16_f32 v2, v0, s0
	v_lshl_add_u64 v[0:1], v[128:129], 0, s[48:49]
	s_mov_b32 s48, 0x88000
	s_nop 0
	global_store_short v[0:1], v2, off offset:3072
	v_mul_f32_e32 v0, 0xbfb8aa3b, v19
	v_exp_f32_e32 v0, v0
	s_nop 0
	v_add_f32_e32 v0, 1.0, v0
	v_rcp_f32_e32 v0, v0
	s_nop 0
	v_mul_f32_e32 v0, v19, v0
	v_mul_f32_e32 v0, v3, v0
	v_cvt_pk_bf16_f32 v2, v0, s0
	v_lshl_add_u64 v[0:1], v[128:129], 0, s[48:49]
	global_store_short v[0:1], v2, off offset:512
	v_mul_f32_e32 v0, 0xbfb8aa3b, v20
	v_exp_f32_e32 v0, v0
	s_mov_b32 s48, 0x8f000
	v_add_f32_e32 v0, 1.0, v0
	v_rcp_f32_e32 v0, v0
	s_nop 0
	v_mul_f32_e32 v0, v20, v0
	v_mul_f32_e32 v0, v4, v0
	v_cvt_pk_bf16_f32 v2, v0, s0
	v_lshl_add_u64 v[0:1], v[128:129], 0, s[48:49]
	s_mov_b32 s48, 0x90000
	s_nop 0
	global_store_short v[0:1], v2, off
	v_mul_f32_e32 v0, 0xbfb8aa3b, v21
	v_exp_f32_e32 v0, v0
	s_nop 0
	v_add_f32_e32 v0, 1.0, v0
	v_rcp_f32_e32 v0, v0
	s_nop 0
	v_mul_f32_e32 v0, v21, v0
	v_mul_f32_e32 v0, v5, v0
	v_cvt_pk_bf16_f32 v2, v0, s0
	v_lshl_add_u64 v[0:1], v[128:129], 0, s[48:49]
	s_mov_b32 s48, 0x91000
	s_nop 0
	global_store_short v[0:1], v2, off offset:1536
	v_mul_f32_e32 v0, 0xbfb8aa3b, v22
	v_exp_f32_e32 v0, v0
	s_nop 0
	v_add_f32_e32 v0, 1.0, v0
	v_rcp_f32_e32 v0, v0
	s_nop 0
	v_mul_f32_e32 v0, v22, v0
	v_mul_f32_e32 v0, v6, v0
	v_cvt_pk_bf16_f32 v2, v0, s0
	v_lshl_add_u64 v[0:1], v[128:129], 0, s[48:49]
	s_mov_b32 s48, 0x93000
	s_nop 0
	global_store_short v[0:1], v2, off offset:3072
	v_mul_f32_e32 v0, 0xbfb8aa3b, v23
	v_exp_f32_e32 v0, v0
	s_nop 0
	v_add_f32_e32 v0, 1.0, v0
	v_rcp_f32_e32 v0, v0
	s_nop 0
	v_mul_f32_e32 v0, v23, v0
	v_mul_f32_e32 v0, v7, v0
	v_cvt_pk_bf16_f32 v2, v0, s0
	v_lshl_add_u64 v[0:1], v[128:129], 0, s[48:49]
	global_store_short v[0:1], v2, off offset:512
	v_mul_f32_e32 v0, 0xbfb8aa3b, v24
	v_exp_f32_e32 v0, v0
	s_mov_b32 s48, 0x9a000
	v_add_f32_e32 v0, 1.0, v0
	v_rcp_f32_e32 v0, v0
	s_nop 0
	v_mul_f32_e32 v0, v24, v0
	v_mul_f32_e32 v0, v8, v0
	v_cvt_pk_bf16_f32 v2, v0, s0
	v_lshl_add_u64 v[0:1], v[128:129], 0, s[48:49]
	s_mov_b32 s48, 0x9b000
	s_nop 0
	global_store_short v[0:1], v2, off
	v_mul_f32_e32 v0, 0xbfb8aa3b, v25
	v_exp_f32_e32 v0, v0
	s_nop 0
	v_add_f32_e32 v0, 1.0, v0
	v_rcp_f32_e32 v0, v0
	s_nop 0
	v_mul_f32_e32 v0, v25, v0
	v_mul_f32_e32 v0, v9, v0
	v_cvt_pk_bf16_f32 v2, v0, s0
	v_lshl_add_u64 v[0:1], v[128:129], 0, s[48:49]
	s_mov_b32 s48, 0x9c000
	s_nop 0
	global_store_short v[0:1], v2, off offset:1536
	v_mul_f32_e32 v0, 0xbfb8aa3b, v26
	v_exp_f32_e32 v0, v0
	s_nop 0
	v_add_f32_e32 v0, 1.0, v0
	v_rcp_f32_e32 v0, v0
	s_nop 0
	v_mul_f32_e32 v0, v26, v0
	v_mul_f32_e32 v0, v10, v0
	v_cvt_pk_bf16_f32 v2, v0, s0
	v_lshl_add_u64 v[0:1], v[128:129], 0, s[48:49]
	s_mov_b32 s48, 0x9e000
	s_nop 0
	global_store_short v[0:1], v2, off offset:3072
	v_mul_f32_e32 v0, 0xbfb8aa3b, v27
	v_exp_f32_e32 v0, v0
	s_nop 0
	v_add_f32_e32 v0, 1.0, v0
	v_rcp_f32_e32 v0, v0
	s_nop 0
	v_mul_f32_e32 v0, v27, v0
	v_mul_f32_e32 v0, v11, v0
	v_cvt_pk_bf16_f32 v2, v0, s0
	v_lshl_add_u64 v[0:1], v[128:129], 0, s[48:49]
	global_store_short v[0:1], v2, off offset:512
	v_mul_f32_e32 v0, 0xbfb8aa3b, v28
	v_exp_f32_e32 v0, v0
	s_mov_b32 s48, 0xa5000
	v_add_f32_e32 v0, 1.0, v0
	v_rcp_f32_e32 v0, v0
	s_nop 0
	v_mul_f32_e32 v0, v28, v0
	v_mul_f32_e32 v0, v12, v0
	v_cvt_pk_bf16_f32 v2, v0, s0
	v_lshl_add_u64 v[0:1], v[128:129], 0, s[48:49]
	s_mov_b32 s48, 0xa6000
	s_nop 0
	global_store_short v[0:1], v2, off
	v_mul_f32_e32 v0, 0xbfb8aa3b, v29
	v_exp_f32_e32 v0, v0
	s_nop 0
	v_add_f32_e32 v0, 1.0, v0
	v_rcp_f32_e32 v0, v0
	s_nop 0
	v_mul_f32_e32 v0, v29, v0
	v_mul_f32_e32 v0, v13, v0
	v_cvt_pk_bf16_f32 v2, v0, s0
	v_lshl_add_u64 v[0:1], v[128:129], 0, s[48:49]
	s_mov_b32 s48, 0xa7000
	s_nop 0
	global_store_short v[0:1], v2, off offset:1536
	v_mul_f32_e32 v0, 0xbfb8aa3b, v30
	v_exp_f32_e32 v0, v0
	s_nop 0
	v_add_f32_e32 v0, 1.0, v0
	v_rcp_f32_e32 v0, v0
	s_nop 0
	v_mul_f32_e32 v0, v30, v0
	v_mul_f32_e32 v0, v14, v0
	v_cvt_pk_bf16_f32 v2, v0, s0
	v_lshl_add_u64 v[0:1], v[128:129], 0, s[48:49]
	global_store_short v[0:1], v2, off offset:3072
	v_mul_f32_e32 v0, 0xbfb8aa3b, v31
	v_exp_f32_e32 v0, v0
	s_nop 0
	v_add_f32_e32 v0, 1.0, v0
	v_rcp_f32_e32 v0, v0
	s_nop 0
	v_mul_f32_e32 v0, v31, v0
	v_mul_f32_e32 v0, v15, v0
	v_cvt_pk_bf16_f32 v2, v0, s0
	v_add_co_u32_e32 v0, vcc, 0xa9000, v128
	s_nop 1
	v_addc_co_u32_e32 v1, vcc, 0, v129, vcc
	global_store_short v[0:1], v2, off offset:512
	s_add_i32 s58, s58, 1
	s_mul_i32 s48, s58, s86
	s_add_i32 s48, s48, s87
	s_cmpk_lt_u32 s48, 0x420
	s_cbranch_scc0 .LBB0_183

; DEV float silu(float x) { return x * sigm(x); }
; template <bool RES, class Epi>
; DEV void gemm_tile_x(const bf16_t* A0, int lda0, const bf16_t* A1, int lda1, int ksplit,
;                      const bf16_t* Bt, int ldb, int K, char* smem, const float* resb, Epi epi) {
;     ...
;       for (int r8 = 0; r8 < 8; ++r8) {
;         const int r = rh * 8 + r8;
;         const int ru = mi * 32 + (r & 3) + 8 * (r >> 2);
;         if (RES) epi(ru, rl, col, acc[mi][0][r], acc[mi][1][r], x0[r8], x1[r8]);
;         else epi(ru, rl, col, acc[mi][0][r], acc[mi][1][r], 0.f, 0.f);
;         if ((r8 & 3) == 3) __builtin_amdgcn_sched_barrier(0);
; DEV void phase_ffn_in(const Params& p, const bf16_t* wt, char* smem) {
;     ...
;               [&](int ru, int rl, int c, float v0, float v1) {
;                 (hb + ru * DFF)[(unsigned)(rl * DFF + (c >> 6) * 32 + (c & 31))] = f2bf(silu(v0) * v1);
;               });
.LBB0_3200:
	s_waitcnt vmcnt(5)
	v_mul_f32_e32 v128, 0xbfb8aa3b, v112
	v_exp_f32_e32 v128, v128
	v_mul_f32_e32 v129, 0xbfb8aa3b, v113
	v_exp_f32_e32 v129, v129
	s_lshl_b32 s52, s52, 6
	v_add_f32_e32 v128, 1.0, v128
	v_rcp_f32_e32 v128, v128
	s_mul_hi_u32 s54, s48, 0x160000
	s_mul_i32 s48, s48, 0x160000
	s_ashr_i32 s53, s52, 31
	v_mul_f32_e32 v112, v112, v128
	s_add_u32 s48, s70, s48
	v_mul_f32_e32 v96, v96, v112
	v_add_f32_e32 v112, 1.0, v129
	s_addc_u32 s54, s71, s54
	s_lshl_b64 s[52:53], s[52:53], 1
	v_rcp_f32_e32 v112, v112
	s_add_u32 s52, s48, s52
	s_addc_u32 s53, s54, s53
	v_cvt_pk_bf16_f32 v96, v96, s0
	v_lshl_add_u64 v[128:129], v[182:183], 1, s[52:53]
	global_store_short v[128:129], v96, off
	v_mul_f32_e32 v96, v113, v112
	v_mul_f32_e32 v112, 0xbfb8aa3b, v114
	v_exp_f32_e32 v112, v112
	v_mul_f32_e32 v96, v97, v96
	v_cvt_pk_bf16_f32 v113, v96, s0
	s_movk_i32 s48, 0x1000
	v_add_f32_e32 v96, 1.0, v112
	v_rcp_f32_e32 v112, v96
	v_lshl_add_u64 v[96:97], v[128:129], 0, s[48:49]
	s_movk_i32 s48, 0x2000
	s_nop 0
	global_store_short v[96:97], v113, off offset:1536
	v_mul_f32_e32 v97, 0xbfb8aa3b, v115
	v_exp_f32_e32 v97, v97
	v_mul_f32_e32 v96, v114, v112
	v_mul_f32_e32 v96, v98, v96
	v_cvt_pk_bf16_f32 v98, v96, s0
	v_add_f32_e32 v96, 1.0, v97
	v_rcp_f32_e32 v112, v96
	v_lshl_add_u64 v[96:97], v[128:129], 0, s[48:49]
	s_movk_i32 s48, 0x4000
	s_nop 0
	global_store_short v[96:97], v98, off offset:3072
	v_mul_f32_e32 v96, v115, v112
	v_mul_f32_e32 v96, v99, v96
	v_cvt_pk_bf16_f32 v98, v96, s0
	v_lshl_add_u64 v[96:97], v[128:129], 0, s[48:49]
	global_store_short v[96:97], v98, off offset:512
	v_mul_f32_e32 v96, 0xbfb8aa3b, v116
	v_exp_f32_e32 v96, v96
	v_mul_f32_e32 v97, 0xbfb8aa3b, v117
	v_exp_f32_e32 v97, v97
	s_mov_b32 s48, 0xb000
	v_add_f32_e32 v96, 1.0, v96
	v_rcp_f32_e32 v96, v96
	v_add_f32_e32 v97, 1.0, v97
	v_rcp_f32_e32 v98, v97
	v_mul_f32_e32 v96, v116, v96
	v_mul_f32_e32 v96, v100, v96
	v_cvt_pk_bf16_f32 v99, v96, s0
	v_lshl_add_u64 v[96:97], v[128:129], 0, s[48:49]
	s_mov_b32 s48, 0xc000
	s_nop 0
	global_store_short v[96:97], v99, off
	v_mul_f32_e32 v97, 0xbfb8aa3b, v118
	v_exp_f32_e32 v97, v97
	v_mul_f32_e32 v96, v117, v98
	v_mul_f32_e32 v96, v101, v96
	v_cvt_pk_bf16_f32 v98, v96, s0
	v_add_f32_e32 v96, 1.0, v97
	v_rcp_f32_e32 v99, v96
	v_lshl_add_u64 v[96:97], v[128:129], 0, s[48:49]
	s_mov_b32 s48, 0xd000
	s_nop 0
	global_store_short v[96:97], v98, off offset:1536
	v_mul_f32_e32 v97, 0xbfb8aa3b, v119
	v_exp_f32_e32 v97, v97
	v_mul_f32_e32 v96, v118, v99
	v_mul_f32_e32 v96, v102, v96
	v_cvt_pk_bf16_f32 v98, v96, s0
	v_add_f32_e32 v96, 1.0, v97
	v_rcp_f32_e32 v99, v96
	v_lshl_add_u64 v[96:97], v[128:129], 0, s[48:49]
	s_mov_b32 s48, 0xf000
	s_nop 0
	global_store_short v[96:97], v98, off offset:3072
	v_mul_f32_e32 v96, v119, v99
	v_mul_f32_e32 v96, v103, v96
	v_cvt_pk_bf16_f32 v98, v96, s0
	v_lshl_add_u64 v[96:97], v[128:129], 0, s[48:49]
	global_store_short v[96:97], v98, off offset:512
	v_mul_f32_e32 v96, 0xbfb8aa3b, v120
	v_exp_f32_e32 v96, v96
	v_mul_f32_e32 v97, 0xbfb8aa3b, v121
	v_exp_f32_e32 v97, v97
	s_mov_b32 s48, 0x16000
	v_add_f32_e32 v96, 1.0, v96
	v_rcp_f32_e32 v96, v96
	v_add_f32_e32 v97, 1.0, v97
	v_rcp_f32_e32 v98, v97
	v_mul_f32_e32 v96, v120, v96
	v_mul_f32_e32 v96, v104, v96
	v_cvt_pk_bf16_f32 v99, v96, s0
	v_lshl_add_u64 v[96:97], v[128:129], 0, s[48:49]
	s_mov_b32 s48, 0x17000
	s_nop 0
	global_store_short v[96:97], v99, off
	v_mul_f32_e32 v97, 0xbfb8aa3b, v122
	v_exp_f32_e32 v97, v97
	v_mul_f32_e32 v96, v121, v98
	v_mul_f32_e32 v96, v105, v96
	v_cvt_pk_bf16_f32 v98, v96, s0
	v_add_f32_e32 v96, 1.0, v97
	v_rcp_f32_e32 v99, v96
	v_lshl_add_u64 v[96:97], v[128:129], 0, s[48:49]
	s_mov_b32 s48, 0x18000
	s_nop 0
	global_store_short v[96:97], v98, off offset:1536
	v_mul_f32_e32 v97, 0xbfb8aa3b, v123
	v_exp_f32_e32 v97, v97
	v_mul_f32_e32 v96, v122, v99
	v_mul_f32_e32 v96, v106, v96
	v_cvt_pk_bf16_f32 v98, v96, s0
	v_add_f32_e32 v96, 1.0, v97
	v_rcp_f32_e32 v99, v96
	v_lshl_add_u64 v[96:97], v[128:129], 0, s[48:49]
	s_mov_b32 s48, 0x1a000
	s_nop 0
	global_store_short v[96:97], v98, off offset:3072
	v_mul_f32_e32 v96, v123, v99
	v_mul_f32_e32 v96, v107, v96
	v_cvt_pk_bf16_f32 v98, v96, s0
	v_lshl_add_u64 v[96:97], v[128:129], 0, s[48:49]
	global_store_short v[96:97], v98, off offset:512
	v_mul_f32_e32 v96, 0xbfb8aa3b, v124
	v_exp_f32_e32 v96, v96
	v_mul_f32_e32 v97, 0xbfb8aa3b, v125
	v_exp_f32_e32 v97, v97
	s_mov_b32 s48, 0x21000
	v_add_f32_e32 v96, 1.0, v96
	v_rcp_f32_e32 v96, v96
	v_add_f32_e32 v97, 1.0, v97
	v_rcp_f32_e32 v98, v97
	v_mul_f32_e32 v96, v124, v96
	v_mul_f32_e32 v96, v108, v96
	v_cvt_pk_bf16_f32 v99, v96, s0
	v_lshl_add_u64 v[96:97], v[128:129], 0, s[48:49]
	s_mov_b32 s48, 0x22000
	s_nop 0
	global_store_short v[96:97], v99, off
	v_mul_f32_e32 v97, 0xbfb8aa3b, v126
	v_exp_f32_e32 v97, v97
	v_mul_f32_e32 v96, v125, v98
	v_mul_f32_e32 v96, v109, v96
	v_cvt_pk_bf16_f32 v98, v96, s0
	v_add_f32_e32 v96, 1.0, v97
	v_rcp_f32_e32 v99, v96
	v_lshl_add_u64 v[96:97], v[128:129], 0, s[48:49]
	s_mov_b32 s48, 0x23000
	s_nop 0
	global_store_short v[96:97], v98, off offset:1536
	v_mul_f32_e32 v97, 0xbfb8aa3b, v127
	v_exp_f32_e32 v97, v97
	v_mul_f32_e32 v96, v126, v99
	v_mul_f32_e32 v96, v110, v96
	v_cvt_pk_bf16_f32 v98, v96, s0
	v_add_f32_e32 v96, 1.0, v97
	v_rcp_f32_e32 v99, v96
	v_lshl_add_u64 v[96:97], v[128:129], 0, s[48:49]
	s_mov_b32 s48, 0x25000
	s_nop 0
	global_store_short v[96:97], v98, off offset:3072
	v_mul_f32_e32 v96, v127, v99
	v_mul_f32_e32 v96, v111, v96
	v_cvt_pk_bf16_f32 v98, v96, s0
	v_lshl_add_u64 v[96:97], v[128:129], 0, s[48:49]
	global_store_short v[96:97], v98, off offset:512
; DEV float silu(float x) { return x * sigm(x); }
; template <bool RES, class Epi>
; DEV void gemm_tile_x(const bf16_t* A0, int lda0, const bf16_t* A1, int lda1, int ksplit,
;                      const bf16_t* Bt, int ldb, int K, char* smem, const float* resb, Epi epi) {
;     ...
;       for (int r8 = 0; r8 < 8; ++r8) {
;         const int r = rh * 8 + r8;
;         const int ru = mi * 32 + (r & 3) + 8 * (r >> 2);
;         if (RES) epi(ru, rl, col, acc[mi][0][r], acc[mi][1][r], x0[r8], x1[r8]);
;         else epi(ru, rl, col, acc[mi][0][r], acc[mi][1][r], 0.f, 0.f);
;         if ((r8 & 3) == 3) __builtin_amdgcn_sched_barrier(0);
; DEV void phase_ffn_in(const Params& p, const bf16_t* wt, char* smem) {
;     ...
;               [&](int ru, int rl, int c, float v0, float v1) {
;                 (hb + ru * DFF)[(unsigned)(rl * DFF + (c >> 6) * 32 + (c & 31))] = f2bf(silu(v0) * v1);
;               });
	v_mul_f32_e32 v96, 0xbfb8aa3b, v80
	v_exp_f32_e32 v96, v96
	v_mul_f32_e32 v97, 0xbfb8aa3b, v81
	v_exp_f32_e32 v97, v97
	s_mov_b32 s48, 0x2c000
	v_add_f32_e32 v96, 1.0, v96
	v_rcp_f32_e32 v96, v96
	v_add_f32_e32 v97, 1.0, v97
	v_rcp_f32_e32 v98, v97
	v_mul_f32_e32 v80, v80, v96
	v_mul_f32_e32 v64, v64, v80
	v_mul_f32_e32 v80, 0xbfb8aa3b, v82
	v_lshl_add_u64 v[96:97], v[128:129], 0, s[48:49]
	v_exp_f32_e32 v80, v80
	v_cvt_pk_bf16_f32 v64, v64, s0
	global_store_short v[96:97], v64, off
	v_mul_f32_e32 v64, v81, v98
	v_mul_f32_e32 v64, v65, v64
	v_cvt_pk_bf16_f32 v81, v64, s0
	s_mov_b32 s48, 0x2d000
	v_add_f32_e32 v64, 1.0, v80
	v_rcp_f32_e32 v80, v64
	v_lshl_add_u64 v[64:65], v[128:129], 0, s[48:49]
	s_mov_b32 s48, 0x2e000
	s_nop 0
	global_store_short v[64:65], v81, off offset:1536
	v_mul_f32_e32 v65, 0xbfb8aa3b, v83
	v_exp_f32_e32 v65, v65
	v_mul_f32_e32 v64, v82, v80
	v_mul_f32_e32 v64, v66, v64
	v_cvt_pk_bf16_f32 v66, v64, s0
	v_add_f32_e32 v64, 1.0, v65
	v_rcp_f32_e32 v80, v64
	v_lshl_add_u64 v[64:65], v[128:129], 0, s[48:49]
	s_mov_b32 s48, 0x30000
	s_nop 0
	global_store_short v[64:65], v66, off offset:3072
	v_mul_f32_e32 v64, v83, v80
	v_mul_f32_e32 v64, v67, v64
	v_cvt_pk_bf16_f32 v66, v64, s0
	v_lshl_add_u64 v[64:65], v[128:129], 0, s[48:49]
	global_store_short v[64:65], v66, off offset:512
	v_mul_f32_e32 v64, 0xbfb8aa3b, v84
	v_exp_f32_e32 v64, v64
	v_mul_f32_e32 v65, 0xbfb8aa3b, v85
	v_exp_f32_e32 v65, v65
	s_mov_b32 s48, 0x37000
	v_add_f32_e32 v64, 1.0, v64
	v_rcp_f32_e32 v64, v64
	v_add_f32_e32 v65, 1.0, v65
	v_rcp_f32_e32 v66, v65
	v_mul_f32_e32 v64, v84, v64
	v_mul_f32_e32 v64, v68, v64
	v_cvt_pk_bf16_f32 v67, v64, s0
	v_lshl_add_u64 v[64:65], v[128:129], 0, s[48:49]
	s_mov_b32 s48, 0x38000
	s_nop 0
	global_store_short v[64:65], v67, off
	v_mul_f32_e32 v65, 0xbfb8aa3b, v86
	v_exp_f32_e32 v65, v65
	v_mul_f32_e32 v64, v85, v66
	v_mul_f32_e32 v64, v69, v64
	v_cvt_pk_bf16_f32 v66, v64, s0
	v_add_f32_e32 v64, 1.0, v65
	v_rcp_f32_e32 v67, v64
	v_lshl_add_u64 v[64:65], v[128:129], 0, s[48:49]
	s_mov_b32 s48, 0x39000
	s_nop 0
	global_store_short v[64:65], v66, off offset:1536
	v_mul_f32_e32 v65, 0xbfb8aa3b, v87
	v_exp_f32_e32 v65, v65
	v_mul_f32_e32 v64, v86, v67
	v_mul_f32_e32 v64, v70, v64
	v_cvt_pk_bf16_f32 v66, v64, s0
	v_add_f32_e32 v64, 1.0, v65
	v_rcp_f32_e32 v67, v64
	v_lshl_add_u64 v[64:65], v[128:129], 0, s[48:49]
	s_mov_b32 s48, 0x3b000
	s_nop 0
	global_store_short v[64:65], v66, off offset:3072
	v_mul_f32_e32 v64, v87, v67
	v_mul_f32_e32 v64, v71, v64
	v_cvt_pk_bf16_f32 v66, v64, s0
	v_lshl_add_u64 v[64:65], v[128:129], 0, s[48:49]
	global_store_short v[64:65], v66, off offset:512
	v_mul_f32_e32 v64, 0xbfb8aa3b, v88
	v_exp_f32_e32 v64, v64
	v_mul_f32_e32 v65, 0xbfb8aa3b, v89
	v_exp_f32_e32 v65, v65
	s_mov_b32 s48, 0x42000
	v_add_f32_e32 v64, 1.0, v64
	v_rcp_f32_e32 v64, v64
	v_add_f32_e32 v65, 1.0, v65
	v_rcp_f32_e32 v66, v65
	v_mul_f32_e32 v64, v88, v64
	v_mul_f32_e32 v64, v72, v64
	v_cvt_pk_bf16_f32 v67, v64, s0
	v_lshl_add_u64 v[64:65], v[128:129], 0, s[48:49]
	s_mov_b32 s48, 0x43000
	s_nop 0
	global_store_short v[64:65], v67, off
	v_mul_f32_e32 v65, 0xbfb8aa3b, v90
	v_exp_f32_e32 v65, v65
	v_mul_f32_e32 v64, v89, v66
	v_mul_f32_e32 v64, v73, v64
	v_cvt_pk_bf16_f32 v66, v64, s0
	v_add_f32_e32 v64, 1.0, v65
	v_rcp_f32_e32 v67, v64
	v_lshl_add_u64 v[64:65], v[128:129], 0, s[48:49]
	s_mov_b32 s48, 0x44000
	s_nop 0
	global_store_short v[64:65], v66, off offset:1536
	v_mul_f32_e32 v65, 0xbfb8aa3b, v91
	v_exp_f32_e32 v65, v65
	v_mul_f32_e32 v64, v90, v67
	v_mul_f32_e32 v64, v74, v64
	v_cvt_pk_bf16_f32 v66, v64, s0
	v_add_f32_e32 v64, 1.0, v65
	v_rcp_f32_e32 v67, v64
	v_lshl_add_u64 v[64:65], v[128:129], 0, s[48:49]
	s_mov_b32 s48, 0x46000
	s_nop 0
	global_store_short v[64:65], v66, off offset:3072
	v_mul_f32_e32 v64, v91, v67
	v_mul_f32_e32 v64, v75, v64
	v_cvt_pk_bf16_f32 v66, v64, s0
	v_lshl_add_u64 v[64:65], v[128:129], 0, s[48:49]
	global_store_short v[64:65], v66, off offset:512
	v_mul_f32_e32 v64, 0xbfb8aa3b, v92
	v_exp_f32_e32 v64, v64
	v_mul_f32_e32 v65, 0xbfb8aa3b, v93
	v_exp_f32_e32 v65, v65
	s_mov_b32 s48, 0x4d000
	v_add_f32_e32 v64, 1.0, v64
	v_rcp_f32_e32 v64, v64
	v_add_f32_e32 v65, 1.0, v65
	v_rcp_f32_e32 v66, v65
	v_mul_f32_e32 v64, v92, v64
	v_mul_f32_e32 v64, v76, v64
	v_cvt_pk_bf16_f32 v67, v64, s0
	v_lshl_add_u64 v[64:65], v[128:129], 0, s[48:49]
	s_mov_b32 s48, 0x4e000
	s_nop 0
	global_store_short v[64:65], v67, off
	v_mul_f32_e32 v65, 0xbfb8aa3b, v94
	v_exp_f32_e32 v65, v65
	v_mul_f32_e32 v64, v93, v66
	v_mul_f32_e32 v64, v77, v64
	v_cvt_pk_bf16_f32 v66, v64, s0
	v_add_f32_e32 v64, 1.0, v65
	v_rcp_f32_e32 v67, v64
	v_lshl_add_u64 v[64:65], v[128:129], 0, s[48:49]
	s_mov_b32 s48, 0x4f000
	s_nop 0
	global_store_short v[64:65], v66, off offset:1536
	v_mul_f32_e32 v65, 0xbfb8aa3b, v95
	v_exp_f32_e32 v65, v65
	v_mul_f32_e32 v64, v94, v67
	v_mul_f32_e32 v64, v78, v64
	v_cvt_pk_bf16_f32 v66, v64, s0
	v_add_f32_e32 v64, 1.0, v65
	v_rcp_f32_e32 v67, v64
	v_lshl_add_u64 v[64:65], v[128:129], 0, s[48:49]
	s_mov_b32 s48, 0x51000
	s_nop 0
	global_store_short v[64:65], v66, off offset:3072
	v_mul_f32_e32 v64, v95, v67
	v_mul_f32_e32 v64, v79, v64
	v_cvt_pk_bf16_f32 v66, v64, s0
	v_lshl_add_u64 v[64:65], v[128:129], 0, s[48:49]
	global_store_short v[64:65], v66, off offset:512
	v_mul_f32_e32 v64, 0xbfb8aa3b, v48
	v_exp_f32_e32 v64, v64
	v_mul_f32_e32 v65, 0xbfb8aa3b, v49
	v_exp_f32_e32 v65, v65
	s_mov_b32 s48, 0x58000
	v_add_f32_e32 v64, 1.0, v64
	v_rcp_f32_e32 v64, v64
	v_add_f32_e32 v65, 1.0, v65
	v_rcp_f32_e32 v66, v65
	v_mul_f32_e32 v48, v48, v64
	v_mul_f32_e32 v32, v32, v48
	v_mul_f32_e32 v48, 0xbfb8aa3b, v50
; DEV float silu(float x) { return x * sigm(x); }
; template <bool RES, class Epi>
; DEV void gemm_tile_x(const bf16_t* A0, int lda0, const bf16_t* A1, int lda1, int ksplit,
;                      const bf16_t* Bt, int ldb, int K, char* smem, const float* resb, Epi epi) {
;     ...
;       for (int r8 = 0; r8 < 8; ++r8) {
;         const int r = rh * 8 + r8;
;         const int ru = mi * 32 + (r & 3) + 8 * (r >> 2);
;         if (RES) epi(ru, rl, col, acc[mi][0][r], acc[mi][1][r], x0[r8], x1[r8]);
;         else epi(ru, rl, col, acc[mi][0][r], acc[mi][1][r], 0.f, 0.f);
;         if ((r8 & 3) == 3) __builtin_amdgcn_sched_barrier(0);
; DEV void phase_ffn_in(const Params& p, const bf16_t* wt, char* smem) {
;     ...
;               [&](int ru, int rl, int c, float v0, float v1) {
;                 (hb + ru * DFF)[(unsigned)(rl * DFF + (c >> 6) * 32 + (c & 31))] = f2bf(silu(v0) * v1);
;               });
	v_lshl_add_u64 v[64:65], v[128:129], 0, s[48:49]
	v_exp_f32_e32 v48, v48
	v_cvt_pk_bf16_f32 v32, v32, s0
	global_store_short v[64:65], v32, off
	v_mul_f32_e32 v32, v49, v66
	v_mul_f32_e32 v32, v33, v32
	v_cvt_pk_bf16_f32 v49, v32, s0
	s_mov_b32 s48, 0x59000
	v_add_f32_e32 v32, 1.0, v48
	v_rcp_f32_e32 v48, v32
	v_lshl_add_u64 v[32:33], v[128:129], 0, s[48:49]
	s_mov_b32 s48, 0x5a000
	s_nop 0
	global_store_short v[32:33], v49, off offset:1536
	v_mul_f32_e32 v33, 0xbfb8aa3b, v51
	v_exp_f32_e32 v33, v33
	v_mul_f32_e32 v32, v50, v48
	v_mul_f32_e32 v32, v34, v32
	v_cvt_pk_bf16_f32 v34, v32, s0
	v_add_f32_e32 v32, 1.0, v33
	v_rcp_f32_e32 v48, v32
	v_lshl_add_u64 v[32:33], v[128:129], 0, s[48:49]
	s_mov_b32 s48, 0x5c000
	s_nop 0
	global_store_short v[32:33], v34, off offset:3072
	v_mul_f32_e32 v32, v51, v48
	v_mul_f32_e32 v32, v35, v32
	v_cvt_pk_bf16_f32 v34, v32, s0
	v_lshl_add_u64 v[32:33], v[128:129], 0, s[48:49]
	global_store_short v[32:33], v34, off offset:512
	v_mul_f32_e32 v32, 0xbfb8aa3b, v52
	v_exp_f32_e32 v32, v32
	v_mul_f32_e32 v33, 0xbfb8aa3b, v53
	v_exp_f32_e32 v33, v33
	s_mov_b32 s48, 0x63000
	v_add_f32_e32 v32, 1.0, v32
	v_rcp_f32_e32 v32, v32
	v_add_f32_e32 v33, 1.0, v33
	v_rcp_f32_e32 v34, v33
	v_mul_f32_e32 v32, v52, v32
	v_mul_f32_e32 v32, v36, v32
	v_cvt_pk_bf16_f32 v35, v32, s0
	v_lshl_add_u64 v[32:33], v[128:129], 0, s[48:49]
	s_mov_b32 s48, 0x64000
	s_nop 0
	global_store_short v[32:33], v35, off
	v_mul_f32_e32 v33, 0xbfb8aa3b, v54
	v_exp_f32_e32 v33, v33
	v_mul_f32_e32 v32, v53, v34
	v_mul_f32_e32 v32, v37, v32
	v_cvt_pk_bf16_f32 v34, v32, s0
	v_add_f32_e32 v32, 1.0, v33
	v_rcp_f32_e32 v35, v32
	v_lshl_add_u64 v[32:33], v[128:129], 0, s[48:49]
	s_mov_b32 s48, 0x65000
	s_nop 0
	global_store_short v[32:33], v34, off offset:1536
	v_mul_f32_e32 v33, 0xbfb8aa3b, v55
	v_exp_f32_e32 v33, v33
	v_mul_f32_e32 v32, v54, v35
	v_mul_f32_e32 v32, v38, v32
	v_cvt_pk_bf16_f32 v34, v32, s0
	v_add_f32_e32 v32, 1.0, v33
	v_rcp_f32_e32 v35, v32
	v_lshl_add_u64 v[32:33], v[128:129], 0, s[48:49]
	s_mov_b32 s48, 0x67000
	s_nop 0
	global_store_short v[32:33], v34, off offset:3072
	v_mul_f32_e32 v32, v55, v35
	v_mul_f32_e32 v32, v39, v32
	v_cvt_pk_bf16_f32 v34, v32, s0
	v_lshl_add_u64 v[32:33], v[128:129], 0, s[48:49]
	global_store_short v[32:33], v34, off offset:512
	v_mul_f32_e32 v32, 0xbfb8aa3b, v56
	v_exp_f32_e32 v32, v32
	v_mul_f32_e32 v33, 0xbfb8aa3b, v57
	v_exp_f32_e32 v33, v33
	s_mov_b32 s48, 0x6e000
	v_add_f32_e32 v32, 1.0, v32
	v_rcp_f32_e32 v32, v32
	v_add_f32_e32 v33, 1.0, v33
	v_rcp_f32_e32 v34, v33
	v_mul_f32_e32 v32, v56, v32
	v_mul_f32_e32 v32, v40, v32
	v_cvt_pk_bf16_f32 v35, v32, s0
	v_lshl_add_u64 v[32:33], v[128:129], 0, s[48:49]
	s_mov_b32 s48, 0x6f000
	s_nop 0
	global_store_short v[32:33], v35, off
	v_mul_f32_e32 v33, 0xbfb8aa3b, v58
	v_exp_f32_e32 v33, v33
	v_mul_f32_e32 v32, v57, v34
	v_mul_f32_e32 v32, v41, v32
	v_cvt_pk_bf16_f32 v34, v32, s0
	v_add_f32_e32 v32, 1.0, v33
	v_rcp_f32_e32 v35, v32
	v_lshl_add_u64 v[32:33], v[128:129], 0, s[48:49]
	s_mov_b32 s48, 0x70000
	s_nop 0
	global_store_short v[32:33], v34, off offset:1536
	v_mul_f32_e32 v33, 0xbfb8aa3b, v59
	v_exp_f32_e32 v33, v33
	v_mul_f32_e32 v32, v58, v35
	v_mul_f32_e32 v32, v42, v32
	v_cvt_pk_bf16_f32 v34, v32, s0
	v_add_f32_e32 v32, 1.0, v33
	v_rcp_f32_e32 v35, v32
	v_lshl_add_u64 v[32:33], v[128:129], 0, s[48:49]
	s_mov_b32 s48, 0x72000
	s_nop 0
	global_store_short v[32:33], v34, off offset:3072
	v_mul_f32_e32 v32, v59, v35
	v_mul_f32_e32 v32, v43, v32
	v_cvt_pk_bf16_f32 v34, v32, s0
	v_lshl_add_u64 v[32:33], v[128:129], 0, s[48:49]
	global_store_short v[32:33], v34, off offset:512
	v_mul_f32_e32 v32, 0xbfb8aa3b, v60
	v_exp_f32_e32 v32, v32
	v_mul_f32_e32 v33, 0xbfb8aa3b, v61
	v_exp_f32_e32 v33, v33
	s_mov_b32 s48, 0x79000
	v_add_f32_e32 v32, 1.0, v32
	v_rcp_f32_e32 v32, v32
	v_add_f32_e32 v33, 1.0, v33
	v_rcp_f32_e32 v34, v33
	v_mul_f32_e32 v32, v60, v32
	v_mul_f32_e32 v32, v44, v32
	v_cvt_pk_bf16_f32 v35, v32, s0
	v_lshl_add_u64 v[32:33], v[128:129], 0, s[48:49]
	s_mov_b32 s48, 0x7a000
	s_nop 0
	global_store_short v[32:33], v35, off
	v_mul_f32_e32 v33, 0xbfb8aa3b, v62
	v_exp_f32_e32 v33, v33
	v_mul_f32_e32 v32, v61, v34
	v_mul_f32_e32 v32, v45, v32
	v_cvt_pk_bf16_f32 v34, v32, s0
	v_add_f32_e32 v32, 1.0, v33
	v_rcp_f32_e32 v35, v32
	v_lshl_add_u64 v[32:33], v[128:129], 0, s[48:49]
	s_mov_b32 s48, 0x7b000
	s_nop 0
	global_store_short v[32:33], v34, off offset:1536
	v_mul_f32_e32 v33, 0xbfb8aa3b, v63
	v_exp_f32_e32 v33, v33
	v_mul_f32_e32 v32, v62, v35
	v_mul_f32_e32 v32, v46, v32
	v_cvt_pk_bf16_f32 v34, v32, s0
	v_add_f32_e32 v32, 1.0, v33
	v_rcp_f32_e32 v35, v32
	v_lshl_add_u64 v[32:33], v[128:129], 0, s[48:49]
	s_mov_b32 s48, 0x7d000
	s_nop 0
	global_store_short v[32:33], v34, off offset:3072
	v_mul_f32_e32 v32, v63, v35
	v_mul_f32_e32 v32, v47, v32
	v_cvt_pk_bf16_f32 v34, v32, s0
	v_lshl_add_u64 v[32:33], v[128:129], 0, s[48:49]
	global_store_short v[32:33], v34, off offset:512
	v_mul_f32_e32 v32, 0xbfb8aa3b, v16
	v_exp_f32_e32 v32, v32
	v_mul_f32_e32 v33, 0xbfb8aa3b, v17
	v_exp_f32_e32 v33, v33
; DEV float silu(float x) { return x * sigm(x); }
; DEV bool tile_map(int it, int nct, int& rt, int& ct) {
;   const int bpx = gridDim.x >> 3, xcd = blockIdx.x & 7, j = blockIdx.x >> 3;
;   const int q = j + it * bpx;
;   if (q >= 24 * nct) return false;
; DEV void phase_ffn_in(const Params& p, const bf16_t* wt, char* smem) {
;     ...
;               [&](int ru, int rl, int c, float v0, float v1) {
;                 (hb + ru * DFF)[(unsigned)(rl * DFF + (c >> 6) * 32 + (c & 31))] = f2bf(silu(v0) * v1);
;               });
	s_mov_b32 s48, 0x84000
	v_add_f32_e32 v32, 1.0, v32
	v_rcp_f32_e32 v32, v32
	v_add_f32_e32 v33, 1.0, v33
	v_rcp_f32_e32 v34, v33
	v_mul_f32_e32 v16, v16, v32
	v_mul_f32_e32 v0, v0, v16
	v_mul_f32_e32 v16, 0xbfb8aa3b, v18
	v_lshl_add_u64 v[32:33], v[128:129], 0, s[48:49]
	v_exp_f32_e32 v16, v16
	v_cvt_pk_bf16_f32 v0, v0, s0
	global_store_short v[32:33], v0, off
	v_mul_f32_e32 v0, v17, v34
	v_mul_f32_e32 v0, v1, v0
	v_cvt_pk_bf16_f32 v17, v0, s0
	s_mov_b32 s48, 0x85000
	v_add_f32_e32 v0, 1.0, v16
	v_rcp_f32_e32 v16, v0
	v_lshl_add_u64 v[0:1], v[128:129], 0, s[48:49]
	s_mov_b32 s48, 0x86000
	s_nop 0
	global_store_short v[0:1], v17, off offset:1536
	v_mul_f32_e32 v1, 0xbfb8aa3b, v19
	v_exp_f32_e32 v1, v1
	v_mul_f32_e32 v0, v18, v16
	v_mul_f32_e32 v0, v2, v0
	v_cvt_pk_bf16_f32 v2, v0, s0
	v_add_f32_e32 v0, 1.0, v1
	v_rcp_f32_e32 v16, v0
	v_lshl_add_u64 v[0:1], v[128:129], 0, s[48:49]
	s_mov_b32 s48, 0x88000
	s_nop 0
	global_store_short v[0:1], v2, off offset:3072
	v_mul_f32_e32 v0, v19, v16
	v_mul_f32_e32 v0, v3, v0
	v_cvt_pk_bf16_f32 v2, v0, s0
	v_lshl_add_u64 v[0:1], v[128:129], 0, s[48:49]
	global_store_short v[0:1], v2, off offset:512
	v_mul_f32_e32 v0, 0xbfb8aa3b, v20
	v_exp_f32_e32 v0, v0
	v_mul_f32_e32 v1, 0xbfb8aa3b, v21
	v_exp_f32_e32 v1, v1
	s_mov_b32 s48, 0x8f000
	v_add_f32_e32 v0, 1.0, v0
	v_rcp_f32_e32 v0, v0
	v_add_f32_e32 v1, 1.0, v1
	v_rcp_f32_e32 v2, v1
	v_mul_f32_e32 v0, v20, v0
	v_mul_f32_e32 v0, v4, v0
	v_cvt_pk_bf16_f32 v3, v0, s0
	v_lshl_add_u64 v[0:1], v[128:129], 0, s[48:49]
	s_mov_b32 s48, 0x90000
	s_nop 0
	global_store_short v[0:1], v3, off
	v_mul_f32_e32 v1, 0xbfb8aa3b, v22
	v_exp_f32_e32 v1, v1
	v_mul_f32_e32 v0, v21, v2
	v_mul_f32_e32 v0, v5, v0
	v_cvt_pk_bf16_f32 v2, v0, s0
	v_add_f32_e32 v0, 1.0, v1
	v_rcp_f32_e32 v3, v0
	v_lshl_add_u64 v[0:1], v[128:129], 0, s[48:49]
	s_mov_b32 s48, 0x91000
	s_nop 0
	global_store_short v[0:1], v2, off offset:1536
	v_mul_f32_e32 v1, 0xbfb8aa3b, v23
	v_exp_f32_e32 v1, v1
	v_mul_f32_e32 v0, v22, v3
	v_mul_f32_e32 v0, v6, v0
	v_cvt_pk_bf16_f32 v2, v0, s0
	v_add_f32_e32 v0, 1.0, v1
	v_rcp_f32_e32 v3, v0
	v_lshl_add_u64 v[0:1], v[128:129], 0, s[48:49]
	s_mov_b32 s48, 0x93000
	s_nop 0
	global_store_short v[0:1], v2, off offset:3072
	v_mul_f32_e32 v0, v23, v3
	v_mul_f32_e32 v0, v7, v0
	v_cvt_pk_bf16_f32 v2, v0, s0
	v_lshl_add_u64 v[0:1], v[128:129], 0, s[48:49]
	global_store_short v[0:1], v2, off offset:512
	v_mul_f32_e32 v0, 0xbfb8aa3b, v24
	v_exp_f32_e32 v0, v0
	v_mul_f32_e32 v1, 0xbfb8aa3b, v25
	v_exp_f32_e32 v1, v1
	s_mov_b32 s48, 0x9a000
	v_add_f32_e32 v0, 1.0, v0
	v_rcp_f32_e32 v0, v0
	v_add_f32_e32 v1, 1.0, v1
	v_rcp_f32_e32 v2, v1
	v_mul_f32_e32 v0, v24, v0
	v_mul_f32_e32 v0, v8, v0
	v_cvt_pk_bf16_f32 v3, v0, s0
	v_lshl_add_u64 v[0:1], v[128:129], 0, s[48:49]
	s_mov_b32 s48, 0x9b000
	s_nop 0
	global_store_short v[0:1], v3, off
	v_mul_f32_e32 v0, v25, v2
	v_mul_f32_e32 v0, v9, v0
	v_cvt_pk_bf16_f32 v2, v0, s0
	v_mul_f32_e32 v0, 0xbfb8aa3b, v26
	v_exp_f32_e32 v3, v0
	v_lshl_add_u64 v[0:1], v[128:129], 0, s[48:49]
	v_add_f32_e32 v3, 1.0, v3
	s_nop 0
	global_store_short v[0:1], v2, off offset:1536
	v_mul_f32_e32 v0, 0xbfb8aa3b, v27
	v_exp_f32_e32 v0, v0
	v_rcp_f32_e32 v3, v3
	v_add_f32_e32 v0, 1.0, v0
	v_mul_f32_e32 v1, v26, v3
	v_rcp_f32_e32 v3, v0
	v_mul_f32_e32 v1, v10, v1
	v_add_co_u32_e32 v0, vcc, s78, v128
	v_cvt_pk_bf16_f32 v2, v1, s0
	s_nop 0
	v_addc_co_u32_e32 v1, vcc, 0, v129, vcc
	global_store_short v[0:1], v2, off offset:3072
	v_mul_f32_e32 v0, v27, v3
	v_mul_f32_e32 v0, v11, v0
	v_cvt_pk_bf16_f32 v2, v0, s0
	v_add_co_u32_e32 v0, vcc, s79, v128
	s_nop 1
	v_addc_co_u32_e32 v1, vcc, 0, v129, vcc
	global_store_short v[0:1], v2, off offset:512
	v_mul_f32_e32 v0, 0xbfb8aa3b, v28
	v_exp_f32_e32 v0, v0
	v_mul_f32_e32 v3, 0xbfb8aa3b, v29
	v_exp_f32_e32 v3, v3
	v_add_f32_e32 v0, 1.0, v0
	v_rcp_f32_e32 v2, v0
	v_add_co_u32_e32 v0, vcc, s80, v128
	v_add_f32_e32 v3, 1.0, v3
	v_mul_f32_e32 v2, v28, v2
	v_mul_f32_e32 v2, v12, v2
	v_addc_co_u32_e32 v1, vcc, 0, v129, vcc
	v_cvt_pk_bf16_f32 v2, v2, s0
	global_store_short v[0:1], v2, off
	v_mul_f32_e32 v0, 0xbfb8aa3b, v30
	v_rcp_f32_e32 v3, v3
	v_exp_f32_e32 v0, v0
	v_mul_f32_e32 v1, v29, v3
	v_add_f32_e32 v0, 1.0, v0
	v_mul_f32_e32 v1, v13, v1
	v_rcp_f32_e32 v3, v0
	v_add_co_u32_e32 v0, vcc, s81, v128
	v_cvt_pk_bf16_f32 v2, v1, s0
	s_nop 0
	v_addc_co_u32_e32 v1, vcc, 0, v129, vcc
	global_store_short v[0:1], v2, off offset:1536
	v_mul_f32_e32 v1, 0xbfb8aa3b, v31
	v_exp_f32_e32 v1, v1
	v_mul_f32_e32 v0, v30, v3
	v_mul_f32_e32 v0, v14, v0
	v_cvt_pk_bf16_f32 v2, v0, s0
	v_add_f32_e32 v1, 1.0, v1
	v_rcp_f32_e32 v3, v1
	v_add_co_u32_e32 v0, vcc, s82, v128
	s_nop 1
	v_addc_co_u32_e32 v1, vcc, 0, v129, vcc
	global_store_short v[0:1], v2, off offset:3072
	v_mul_f32_e32 v0, v31, v3
	v_mul_f32_e32 v0, v15, v0
	v_cvt_pk_bf16_f32 v2, v0, s0
	v_add_co_u32_e32 v0, vcc, 0xa9000, v128
	s_nop 1
	v_addc_co_u32_e32 v1, vcc, 0, v129, vcc
	global_store_short v[0:1], v2, off offset:512
	s_add_i32 s58, s58, 1
	s_mul_i32 s48, s58, s72
	s_add_i32 s48, s48, s73
	s_cmpk_lt_u32 s48, 0x420
	s_cbranch_scc0 .LBB0_3209
